# P5 forward substitution: all 8 waves work (one right-hand side per thread, formerly idle waves take w), v_fmac_f32_dpp, LDS reads one row ahead; same arithmetic order
# speedup vs baseline: 1.0422x; 1.0104x over previous
; __device__ __forceinline__ float bf2f(unsigned short b) { return __uint_as_float((unsigned)b << 16); }
; __device__ __forceinline__ unsigned short f2bf(float f) { return (unsigned short)(cvt_pk_bf16(f, 0.f) & 0xffffu); }
; __device__ __forceinline__ void prep_unit(const int PREP_STEPS, LAS unsigned char* lds, int uidx, bf16* Qg, bf16* Kg, bf16* Vg, bf16* KT, bf16* QK, const bf16* HALO, const float* wconv, const float* BETA, const float* GG, float* GC) {
;     ...
;     if (PREP_STEPS & 4) {
;         const bool active = hb == 0 ? (tl < 128) : (tl >= 128);
;         if (active) {
;         const int c = tl & 127;
;         bf16* dstu = Vg + (size_t)m0 * D + h * 128 + c; bf16* dstw = Kg + (size_t)m0 * D + h * 128 + c;
; #pragma unroll 1
;         for (int I = 0; I < 4; ++I) {
;             float au[16], aw[16];
; #pragma unroll
;             for (int r = 0; r < 16; ++r) { au[r] = bf2f(Vs[(16 * I + r) * 136 + c]) * betas[16 * I + r]; aw[r] = bf2f(Ks[(16 * I + r) * 136 + c]) * egcs[16 * I + r]; }
;             const int l16 = lane & 15;
; #pragma unroll 2
;             for (int j = 0; j < 16 * I; ++j) {
;                 const float xu = bf2f(Vs[j * 136 + c]), xw = bf2f(Ks[j * 136 + c]);
;                 const int av = __builtin_bit_cast(int, Af[j * 68 + 16 * I + l16]);
;                 Rows16<0>::run(av, xu, xw, au, aw, -1);
;             }
; #pragma unroll
;             for (int q = 0; q < 15; ++q) {
;                 const float xu = au[q], xw = aw[q];
;                 const int av = __builtin_bit_cast(int, Af[(16 * I + q) * 68 + 16 * I + l16]);
;                 Rows16<0>::run(av, xu, xw, au, aw, q);
;             }
; #pragma unroll
;             for (int r = 0; r < 16; ++r) { const unsigned short ub = f2bf(au[r]), wb = f2bf(aw[r]); Vs[(16 * I + r) * 136 + c] = ub; Ks[(16 * I + r) * 136 + c] = wb;
;                 dstu[(size_t)(16 * I + r) * D] = ub; dstw[(size_t)(16 * I + r) * D] = wb; }
;         }
;         }
;     }
.LBB0_762:
	s_waitcnt lgkmcnt(0)
	s_barrier
	s_mov_b64 s[6:7], exec
	s_and_b64 s[0:1], s[4:5], exec
	s_cmp_lg_u64 s[0:1], 0
	s_cselect_b32 s12, s10, s8
	s_cselect_b32 s13, s11, s9
	s_mov_b32 s14, 0x4400
	s_cselect_b32 s14, 0x8800, s14
	s_mov_b32 s15, 0x11200
	s_cselect_b32 s15, 0x11100, s15
	s_lshl_b32 s0, s82, 8
	s_add_u32 s12, s12, s0
	s_addc_u32 s13, s13, 0
	v_lshlrev_b32_e32 v16, 1, v56
	v_add_u32_e32 v16, v16, v110
	v_add_u32_e32 v16, s14, v16
	v_mov_b32_e32 v17, v16
	v_add_u32_e32 v48, s15, v110
	v_lshlrev_b32_e32 v49, 11, v70
	v_lshl_add_u32 v49, v56, 1, v49
	s_mov_b32 s1, 0
.Lfs_I:
	ds_read_b128 v[40:43], v48
	ds_read_b128 v[44:47], v48 offset:16
	ds_read_u16 v20, v17
	ds_read_u16 v21, v17 offset:272
	ds_read_u16 v22, v17 offset:544
	ds_read_u16 v23, v17 offset:816
	ds_read_u16 v24, v17 offset:1088
	ds_read_u16 v25, v17 offset:1360
	ds_read_u16 v26, v17 offset:1632
	ds_read_u16 v27, v17 offset:1904
	s_waitcnt lgkmcnt(0)
	v_lshlrev_b32_e32 v20, 16, v20
	v_lshlrev_b32_e32 v21, 16, v21
	v_lshlrev_b32_e32 v22, 16, v22
	v_lshlrev_b32_e32 v23, 16, v23
	v_lshlrev_b32_e32 v24, 16, v24
	v_lshlrev_b32_e32 v25, 16, v25
	v_lshlrev_b32_e32 v26, 16, v26
	v_lshlrev_b32_e32 v27, 16, v27
	v_mul_f32_e32 v0, v20, v40
	v_mul_f32_e32 v1, v21, v41
	v_mul_f32_e32 v2, v22, v42
	v_mul_f32_e32 v3, v23, v43
	v_mul_f32_e32 v4, v24, v44
	v_mul_f32_e32 v5, v25, v45
	v_mul_f32_e32 v6, v26, v46
	v_mul_f32_e32 v7, v27, v47
	ds_read_b128 v[40:43], v48 offset:32
	ds_read_b128 v[44:47], v48 offset:48
	ds_read_u16 v20, v17 offset:2176
	ds_read_u16 v21, v17 offset:2448
	ds_read_u16 v22, v17 offset:2720
	ds_read_u16 v23, v17 offset:2992
	ds_read_u16 v24, v17 offset:3264
	ds_read_u16 v25, v17 offset:3536
	ds_read_u16 v26, v17 offset:3808
	ds_read_u16 v27, v17 offset:4080
	s_waitcnt lgkmcnt(0)
	v_lshlrev_b32_e32 v20, 16, v20
	v_lshlrev_b32_e32 v21, 16, v21
	v_lshlrev_b32_e32 v22, 16, v22
	v_lshlrev_b32_e32 v23, 16, v23
	v_lshlrev_b32_e32 v24, 16, v24
	v_lshlrev_b32_e32 v25, 16, v25
	v_lshlrev_b32_e32 v26, 16, v26
	v_lshlrev_b32_e32 v27, 16, v27
	v_mul_f32_e32 v8, v20, v40
	v_mul_f32_e32 v9, v21, v41
	v_mul_f32_e32 v10, v22, v42
	v_mul_f32_e32 v11, v23, v43
	v_mul_f32_e32 v12, v24, v44
	v_mul_f32_e32 v13, v25, v45
	v_mul_f32_e32 v14, v26, v46
	v_mul_f32_e32 v15, v27, v47
	s_cmp_eq_u32 s1, 0
	s_cbranch_scc1 .Lfs_q
	s_lshl_b32 s0, s1, 4
	s_lshl_b32 s8, s1, 6
	v_mov_b32_e32 v18, v16
	v_add_u32_e32 v19, s8, v145
	ds_read_u16 v36, v18
	ds_read_b32 v37, v19
.Lfs_j:
	s_waitcnt lgkmcnt(0)
	v_lshlrev_b32_e32 v38, 16, v36
	v_mov_b32_e32 v39, v37
	v_add_u32_e32 v18, 0x110, v18
	v_add_u32_e32 v19, 0x110, v19
	ds_read_u16 v36, v18
	ds_read_b32 v37, v19
	v_fmac_f32_dpp v0, v39, v38 row_newbcast:0 row_mask:0xf bank_mask:0xf bound_ctrl:1
	v_fmac_f32_dpp v1, v39, v38 row_newbcast:1 row_mask:0xf bank_mask:0xf bound_ctrl:1
	v_fmac_f32_dpp v2, v39, v38 row_newbcast:2 row_mask:0xf bank_mask:0xf bound_ctrl:1
	v_fmac_f32_dpp v3, v39, v38 row_newbcast:3 row_mask:0xf bank_mask:0xf bound_ctrl:1
	v_fmac_f32_dpp v4, v39, v38 row_newbcast:4 row_mask:0xf bank_mask:0xf bound_ctrl:1
	v_fmac_f32_dpp v5, v39, v38 row_newbcast:5 row_mask:0xf bank_mask:0xf bound_ctrl:1
	v_fmac_f32_dpp v6, v39, v38 row_newbcast:6 row_mask:0xf bank_mask:0xf bound_ctrl:1
	v_fmac_f32_dpp v7, v39, v38 row_newbcast:7 row_mask:0xf bank_mask:0xf bound_ctrl:1
	v_fmac_f32_dpp v8, v39, v38 row_newbcast:8 row_mask:0xf bank_mask:0xf bound_ctrl:1
	v_fmac_f32_dpp v9, v39, v38 row_newbcast:9 row_mask:0xf bank_mask:0xf bound_ctrl:1
	v_fmac_f32_dpp v10, v39, v38 row_newbcast:10 row_mask:0xf bank_mask:0xf bound_ctrl:1
	v_fmac_f32_dpp v11, v39, v38 row_newbcast:11 row_mask:0xf bank_mask:0xf bound_ctrl:1
	v_fmac_f32_dpp v12, v39, v38 row_newbcast:12 row_mask:0xf bank_mask:0xf bound_ctrl:1
	v_fmac_f32_dpp v13, v39, v38 row_newbcast:13 row_mask:0xf bank_mask:0xf bound_ctrl:1
	v_fmac_f32_dpp v14, v39, v38 row_newbcast:14 row_mask:0xf bank_mask:0xf bound_ctrl:1
	v_fmac_f32_dpp v15, v39, v38 row_newbcast:15 row_mask:0xf bank_mask:0xf bound_ctrl:1
	s_sub_i32 s0, s0, 1
	s_cmp_lg_u32 s0, 0
	s_cbranch_scc1 .Lfs_j
	s_waitcnt lgkmcnt(0)
.Lfs_q:
	s_mul_i32 s0, s1, 0x1140
	v_add_u32_e32 v19, s0, v145
	ds_read_b32 v20, v19
	ds_read_b32 v21, v19 offset:272
	ds_read_b32 v22, v19 offset:544
	ds_read_b32 v23, v19 offset:816
	ds_read_b32 v24, v19 offset:1088
	ds_read_b32 v25, v19 offset:1360
	ds_read_b32 v26, v19 offset:1632
	ds_read_b32 v27, v19 offset:1904
	ds_read_b32 v28, v19 offset:2176
	ds_read_b32 v29, v19 offset:2448
	ds_read_b32 v30, v19 offset:2720
	ds_read_b32 v31, v19 offset:2992
	ds_read_b32 v32, v19 offset:3264
	ds_read_b32 v33, v19 offset:3536
	ds_read_b32 v34, v19 offset:3808
	s_waitcnt lgkmcnt(14)
	v_fmac_f32_dpp v1, v20, v0 row_newbcast:1 row_mask:0xf bank_mask:0xf bound_ctrl:1
	v_fmac_f32_dpp v2, v20, v0 row_newbcast:2 row_mask:0xf bank_mask:0xf bound_ctrl:1
	v_fmac_f32_dpp v3, v20, v0 row_newbcast:3 row_mask:0xf bank_mask:0xf bound_ctrl:1
	v_fmac_f32_dpp v4, v20, v0 row_newbcast:4 row_mask:0xf bank_mask:0xf bound_ctrl:1
	v_fmac_f32_dpp v5, v20, v0 row_newbcast:5 row_mask:0xf bank_mask:0xf bound_ctrl:1
	v_fmac_f32_dpp v6, v20, v0 row_newbcast:6 row_mask:0xf bank_mask:0xf bound_ctrl:1
	v_fmac_f32_dpp v7, v20, v0 row_newbcast:7 row_mask:0xf bank_mask:0xf bound_ctrl:1
	v_fmac_f32_dpp v8, v20, v0 row_newbcast:8 row_mask:0xf bank_mask:0xf bound_ctrl:1
	v_fmac_f32_dpp v9, v20, v0 row_newbcast:9 row_mask:0xf bank_mask:0xf bound_ctrl:1
	v_fmac_f32_dpp v10, v20, v0 row_newbcast:10 row_mask:0xf bank_mask:0xf bound_ctrl:1
	v_fmac_f32_dpp v11, v20, v0 row_newbcast:11 row_mask:0xf bank_mask:0xf bound_ctrl:1
	v_fmac_f32_dpp v12, v20, v0 row_newbcast:12 row_mask:0xf bank_mask:0xf bound_ctrl:1
	v_fmac_f32_dpp v13, v20, v0 row_newbcast:13 row_mask:0xf bank_mask:0xf bound_ctrl:1
	v_fmac_f32_dpp v14, v20, v0 row_newbcast:14 row_mask:0xf bank_mask:0xf bound_ctrl:1
	v_fmac_f32_dpp v15, v20, v0 row_newbcast:15 row_mask:0xf bank_mask:0xf bound_ctrl:1
	s_waitcnt lgkmcnt(13)
; __device__ __forceinline__ void prep_unit(const int PREP_STEPS, LAS unsigned char* lds, int uidx, bf16* Qg, bf16* Kg, bf16* Vg, bf16* KT, bf16* QK, const bf16* HALO, const float* wconv, const float* BETA, const float* GG, float* GC) {
;     ...
;             for (int q = 0; q < 15; ++q) {
;                 const float xu = au[q], xw = aw[q];
;                 const int av = __builtin_bit_cast(int, Af[(16 * I + q) * 68 + 16 * I + l16]);
;                 Rows16<0>::run(av, xu, xw, au, aw, q);
;             }
	v_fmac_f32_dpp v2, v21, v1 row_newbcast:2 row_mask:0xf bank_mask:0xf bound_ctrl:1
	v_fmac_f32_dpp v3, v21, v1 row_newbcast:3 row_mask:0xf bank_mask:0xf bound_ctrl:1
	v_fmac_f32_dpp v4, v21, v1 row_newbcast:4 row_mask:0xf bank_mask:0xf bound_ctrl:1
	v_fmac_f32_dpp v5, v21, v1 row_newbcast:5 row_mask:0xf bank_mask:0xf bound_ctrl:1
	v_fmac_f32_dpp v6, v21, v1 row_newbcast:6 row_mask:0xf bank_mask:0xf bound_ctrl:1
	v_fmac_f32_dpp v7, v21, v1 row_newbcast:7 row_mask:0xf bank_mask:0xf bound_ctrl:1
	v_fmac_f32_dpp v8, v21, v1 row_newbcast:8 row_mask:0xf bank_mask:0xf bound_ctrl:1
	v_fmac_f32_dpp v9, v21, v1 row_newbcast:9 row_mask:0xf bank_mask:0xf bound_ctrl:1
	v_fmac_f32_dpp v10, v21, v1 row_newbcast:10 row_mask:0xf bank_mask:0xf bound_ctrl:1
	v_fmac_f32_dpp v11, v21, v1 row_newbcast:11 row_mask:0xf bank_mask:0xf bound_ctrl:1
	v_fmac_f32_dpp v12, v21, v1 row_newbcast:12 row_mask:0xf bank_mask:0xf bound_ctrl:1
	v_fmac_f32_dpp v13, v21, v1 row_newbcast:13 row_mask:0xf bank_mask:0xf bound_ctrl:1
	v_fmac_f32_dpp v14, v21, v1 row_newbcast:14 row_mask:0xf bank_mask:0xf bound_ctrl:1
	v_fmac_f32_dpp v15, v21, v1 row_newbcast:15 row_mask:0xf bank_mask:0xf bound_ctrl:1
	s_waitcnt lgkmcnt(12)
	v_fmac_f32_dpp v3, v22, v2 row_newbcast:3 row_mask:0xf bank_mask:0xf bound_ctrl:1
	v_fmac_f32_dpp v4, v22, v2 row_newbcast:4 row_mask:0xf bank_mask:0xf bound_ctrl:1
	v_fmac_f32_dpp v5, v22, v2 row_newbcast:5 row_mask:0xf bank_mask:0xf bound_ctrl:1
	v_fmac_f32_dpp v6, v22, v2 row_newbcast:6 row_mask:0xf bank_mask:0xf bound_ctrl:1
	v_fmac_f32_dpp v7, v22, v2 row_newbcast:7 row_mask:0xf bank_mask:0xf bound_ctrl:1
	v_fmac_f32_dpp v8, v22, v2 row_newbcast:8 row_mask:0xf bank_mask:0xf bound_ctrl:1
	v_fmac_f32_dpp v9, v22, v2 row_newbcast:9 row_mask:0xf bank_mask:0xf bound_ctrl:1
	v_fmac_f32_dpp v10, v22, v2 row_newbcast:10 row_mask:0xf bank_mask:0xf bound_ctrl:1
	v_fmac_f32_dpp v11, v22, v2 row_newbcast:11 row_mask:0xf bank_mask:0xf bound_ctrl:1
	v_fmac_f32_dpp v12, v22, v2 row_newbcast:12 row_mask:0xf bank_mask:0xf bound_ctrl:1
	v_fmac_f32_dpp v13, v22, v2 row_newbcast:13 row_mask:0xf bank_mask:0xf bound_ctrl:1
	v_fmac_f32_dpp v14, v22, v2 row_newbcast:14 row_mask:0xf bank_mask:0xf bound_ctrl:1
	v_fmac_f32_dpp v15, v22, v2 row_newbcast:15 row_mask:0xf bank_mask:0xf bound_ctrl:1
	s_waitcnt lgkmcnt(11)
	v_fmac_f32_dpp v4, v23, v3 row_newbcast:4 row_mask:0xf bank_mask:0xf bound_ctrl:1
	v_fmac_f32_dpp v5, v23, v3 row_newbcast:5 row_mask:0xf bank_mask:0xf bound_ctrl:1
	v_fmac_f32_dpp v6, v23, v3 row_newbcast:6 row_mask:0xf bank_mask:0xf bound_ctrl:1
	v_fmac_f32_dpp v7, v23, v3 row_newbcast:7 row_mask:0xf bank_mask:0xf bound_ctrl:1
	v_fmac_f32_dpp v8, v23, v3 row_newbcast:8 row_mask:0xf bank_mask:0xf bound_ctrl:1
	v_fmac_f32_dpp v9, v23, v3 row_newbcast:9 row_mask:0xf bank_mask:0xf bound_ctrl:1
	v_fmac_f32_dpp v10, v23, v3 row_newbcast:10 row_mask:0xf bank_mask:0xf bound_ctrl:1
	v_fmac_f32_dpp v11, v23, v3 row_newbcast:11 row_mask:0xf bank_mask:0xf bound_ctrl:1
	v_fmac_f32_dpp v12, v23, v3 row_newbcast:12 row_mask:0xf bank_mask:0xf bound_ctrl:1
	v_fmac_f32_dpp v13, v23, v3 row_newbcast:13 row_mask:0xf bank_mask:0xf bound_ctrl:1
	v_fmac_f32_dpp v14, v23, v3 row_newbcast:14 row_mask:0xf bank_mask:0xf bound_ctrl:1
	v_fmac_f32_dpp v15, v23, v3 row_newbcast:15 row_mask:0xf bank_mask:0xf bound_ctrl:1
	s_waitcnt lgkmcnt(10)
	v_fmac_f32_dpp v5, v24, v4 row_newbcast:5 row_mask:0xf bank_mask:0xf bound_ctrl:1
	v_fmac_f32_dpp v6, v24, v4 row_newbcast:6 row_mask:0xf bank_mask:0xf bound_ctrl:1
	v_fmac_f32_dpp v7, v24, v4 row_newbcast:7 row_mask:0xf bank_mask:0xf bound_ctrl:1
	v_fmac_f32_dpp v8, v24, v4 row_newbcast:8 row_mask:0xf bank_mask:0xf bound_ctrl:1
	v_fmac_f32_dpp v9, v24, v4 row_newbcast:9 row_mask:0xf bank_mask:0xf bound_ctrl:1
	v_fmac_f32_dpp v10, v24, v4 row_newbcast:10 row_mask:0xf bank_mask:0xf bound_ctrl:1
	v_fmac_f32_dpp v11, v24, v4 row_newbcast:11 row_mask:0xf bank_mask:0xf bound_ctrl:1
	v_fmac_f32_dpp v12, v24, v4 row_newbcast:12 row_mask:0xf bank_mask:0xf bound_ctrl:1
	v_fmac_f32_dpp v13, v24, v4 row_newbcast:13 row_mask:0xf bank_mask:0xf bound_ctrl:1
	v_fmac_f32_dpp v14, v24, v4 row_newbcast:14 row_mask:0xf bank_mask:0xf bound_ctrl:1
	v_fmac_f32_dpp v15, v24, v4 row_newbcast:15 row_mask:0xf bank_mask:0xf bound_ctrl:1
	s_waitcnt lgkmcnt(9)
	v_fmac_f32_dpp v6, v25, v5 row_newbcast:6 row_mask:0xf bank_mask:0xf bound_ctrl:1
	v_fmac_f32_dpp v7, v25, v5 row_newbcast:7 row_mask:0xf bank_mask:0xf bound_ctrl:1
	v_fmac_f32_dpp v8, v25, v5 row_newbcast:8 row_mask:0xf bank_mask:0xf bound_ctrl:1
	v_fmac_f32_dpp v9, v25, v5 row_newbcast:9 row_mask:0xf bank_mask:0xf bound_ctrl:1
	v_fmac_f32_dpp v10, v25, v5 row_newbcast:10 row_mask:0xf bank_mask:0xf bound_ctrl:1
	v_fmac_f32_dpp v11, v25, v5 row_newbcast:11 row_mask:0xf bank_mask:0xf bound_ctrl:1
	v_fmac_f32_dpp v12, v25, v5 row_newbcast:12 row_mask:0xf bank_mask:0xf bound_ctrl:1
	v_fmac_f32_dpp v13, v25, v5 row_newbcast:13 row_mask:0xf bank_mask:0xf bound_ctrl:1
	v_fmac_f32_dpp v14, v25, v5 row_newbcast:14 row_mask:0xf bank_mask:0xf bound_ctrl:1
	v_fmac_f32_dpp v15, v25, v5 row_newbcast:15 row_mask:0xf bank_mask:0xf bound_ctrl:1
	s_waitcnt lgkmcnt(8)
	v_fmac_f32_dpp v7, v26, v6 row_newbcast:7 row_mask:0xf bank_mask:0xf bound_ctrl:1
	v_fmac_f32_dpp v8, v26, v6 row_newbcast:8 row_mask:0xf bank_mask:0xf bound_ctrl:1
	v_fmac_f32_dpp v9, v26, v6 row_newbcast:9 row_mask:0xf bank_mask:0xf bound_ctrl:1
	v_fmac_f32_dpp v10, v26, v6 row_newbcast:10 row_mask:0xf bank_mask:0xf bound_ctrl:1
	v_fmac_f32_dpp v11, v26, v6 row_newbcast:11 row_mask:0xf bank_mask:0xf bound_ctrl:1
	v_fmac_f32_dpp v12, v26, v6 row_newbcast:12 row_mask:0xf bank_mask:0xf bound_ctrl:1
	v_fmac_f32_dpp v13, v26, v6 row_newbcast:13 row_mask:0xf bank_mask:0xf bound_ctrl:1
	v_fmac_f32_dpp v14, v26, v6 row_newbcast:14 row_mask:0xf bank_mask:0xf bound_ctrl:1
	v_fmac_f32_dpp v15, v26, v6 row_newbcast:15 row_mask:0xf bank_mask:0xf bound_ctrl:1
	s_waitcnt lgkmcnt(7)
; __device__ __forceinline__ unsigned short f2bf(float f) { return (unsigned short)(cvt_pk_bf16(f, 0.f) & 0xffffu); }
; __device__ __forceinline__ void prep_unit(const int PREP_STEPS, LAS unsigned char* lds, int uidx, bf16* Qg, bf16* Kg, bf16* Vg, bf16* KT, bf16* QK, const bf16* HALO, const float* wconv, const float* BETA, const float* GG, float* GC) {
;     ...
;             for (int q = 0; q < 15; ++q) {
;                 const float xu = au[q], xw = aw[q];
;                 const int av = __builtin_bit_cast(int, Af[(16 * I + q) * 68 + 16 * I + l16]);
;                 Rows16<0>::run(av, xu, xw, au, aw, q);
;             }
; #pragma unroll
;             for (int r = 0; r < 16; ++r) { const unsigned short ub = f2bf(au[r]), wb = f2bf(aw[r]); Vs[(16 * I + r) * 136 + c] = ub; Ks[(16 * I + r) * 136 + c] = wb;
;                 dstu[(size_t)(16 * I + r) * D] = ub; dstw[(size_t)(16 * I + r) * D] = wb; }
;         }
	v_fmac_f32_dpp v8, v27, v7 row_newbcast:8 row_mask:0xf bank_mask:0xf bound_ctrl:1
	v_fmac_f32_dpp v9, v27, v7 row_newbcast:9 row_mask:0xf bank_mask:0xf bound_ctrl:1
	v_fmac_f32_dpp v10, v27, v7 row_newbcast:10 row_mask:0xf bank_mask:0xf bound_ctrl:1
	v_fmac_f32_dpp v11, v27, v7 row_newbcast:11 row_mask:0xf bank_mask:0xf bound_ctrl:1
	v_fmac_f32_dpp v12, v27, v7 row_newbcast:12 row_mask:0xf bank_mask:0xf bound_ctrl:1
	v_fmac_f32_dpp v13, v27, v7 row_newbcast:13 row_mask:0xf bank_mask:0xf bound_ctrl:1
	v_fmac_f32_dpp v14, v27, v7 row_newbcast:14 row_mask:0xf bank_mask:0xf bound_ctrl:1
	v_fmac_f32_dpp v15, v27, v7 row_newbcast:15 row_mask:0xf bank_mask:0xf bound_ctrl:1
	s_waitcnt lgkmcnt(6)
	v_fmac_f32_dpp v9, v28, v8 row_newbcast:9 row_mask:0xf bank_mask:0xf bound_ctrl:1
	v_fmac_f32_dpp v10, v28, v8 row_newbcast:10 row_mask:0xf bank_mask:0xf bound_ctrl:1
	v_fmac_f32_dpp v11, v28, v8 row_newbcast:11 row_mask:0xf bank_mask:0xf bound_ctrl:1
	v_fmac_f32_dpp v12, v28, v8 row_newbcast:12 row_mask:0xf bank_mask:0xf bound_ctrl:1
	v_fmac_f32_dpp v13, v28, v8 row_newbcast:13 row_mask:0xf bank_mask:0xf bound_ctrl:1
	v_fmac_f32_dpp v14, v28, v8 row_newbcast:14 row_mask:0xf bank_mask:0xf bound_ctrl:1
	v_fmac_f32_dpp v15, v28, v8 row_newbcast:15 row_mask:0xf bank_mask:0xf bound_ctrl:1
	s_waitcnt lgkmcnt(5)
	v_fmac_f32_dpp v10, v29, v9 row_newbcast:10 row_mask:0xf bank_mask:0xf bound_ctrl:1
	v_fmac_f32_dpp v11, v29, v9 row_newbcast:11 row_mask:0xf bank_mask:0xf bound_ctrl:1
	v_fmac_f32_dpp v12, v29, v9 row_newbcast:12 row_mask:0xf bank_mask:0xf bound_ctrl:1
	v_fmac_f32_dpp v13, v29, v9 row_newbcast:13 row_mask:0xf bank_mask:0xf bound_ctrl:1
	v_fmac_f32_dpp v14, v29, v9 row_newbcast:14 row_mask:0xf bank_mask:0xf bound_ctrl:1
	v_fmac_f32_dpp v15, v29, v9 row_newbcast:15 row_mask:0xf bank_mask:0xf bound_ctrl:1
	s_waitcnt lgkmcnt(4)
	v_fmac_f32_dpp v11, v30, v10 row_newbcast:11 row_mask:0xf bank_mask:0xf bound_ctrl:1
	v_fmac_f32_dpp v12, v30, v10 row_newbcast:12 row_mask:0xf bank_mask:0xf bound_ctrl:1
	v_fmac_f32_dpp v13, v30, v10 row_newbcast:13 row_mask:0xf bank_mask:0xf bound_ctrl:1
	v_fmac_f32_dpp v14, v30, v10 row_newbcast:14 row_mask:0xf bank_mask:0xf bound_ctrl:1
	v_fmac_f32_dpp v15, v30, v10 row_newbcast:15 row_mask:0xf bank_mask:0xf bound_ctrl:1
	s_waitcnt lgkmcnt(3)
	v_fmac_f32_dpp v12, v31, v11 row_newbcast:12 row_mask:0xf bank_mask:0xf bound_ctrl:1
	v_fmac_f32_dpp v13, v31, v11 row_newbcast:13 row_mask:0xf bank_mask:0xf bound_ctrl:1
	v_fmac_f32_dpp v14, v31, v11 row_newbcast:14 row_mask:0xf bank_mask:0xf bound_ctrl:1
	v_fmac_f32_dpp v15, v31, v11 row_newbcast:15 row_mask:0xf bank_mask:0xf bound_ctrl:1
	s_waitcnt lgkmcnt(2)
	v_fmac_f32_dpp v13, v32, v12 row_newbcast:13 row_mask:0xf bank_mask:0xf bound_ctrl:1
	v_fmac_f32_dpp v14, v32, v12 row_newbcast:14 row_mask:0xf bank_mask:0xf bound_ctrl:1
	v_fmac_f32_dpp v15, v32, v12 row_newbcast:15 row_mask:0xf bank_mask:0xf bound_ctrl:1
	s_waitcnt lgkmcnt(1)
	v_fmac_f32_dpp v14, v33, v13 row_newbcast:14 row_mask:0xf bank_mask:0xf bound_ctrl:1
	v_fmac_f32_dpp v15, v33, v13 row_newbcast:15 row_mask:0xf bank_mask:0xf bound_ctrl:1
	s_waitcnt lgkmcnt(0)
	v_fmac_f32_dpp v15, v34, v14 row_newbcast:15 row_mask:0xf bank_mask:0xf bound_ctrl:1
	v_cvt_pk_bf16_f32 v20, v0, v0
	v_cvt_pk_bf16_f32 v21, v1, v1
	v_cvt_pk_bf16_f32 v22, v2, v2
	v_cvt_pk_bf16_f32 v23, v3, v3
	v_cvt_pk_bf16_f32 v24, v4, v4
	v_cvt_pk_bf16_f32 v25, v5, v5
	v_cvt_pk_bf16_f32 v26, v6, v6
	v_cvt_pk_bf16_f32 v27, v7, v7
	v_cvt_pk_bf16_f32 v28, v8, v8
	v_cvt_pk_bf16_f32 v29, v9, v9
	v_cvt_pk_bf16_f32 v30, v10, v10
	v_cvt_pk_bf16_f32 v31, v11, v11
	v_cvt_pk_bf16_f32 v32, v12, v12
	v_cvt_pk_bf16_f32 v33, v13, v13
	v_cvt_pk_bf16_f32 v34, v14, v14
	v_cvt_pk_bf16_f32 v35, v15, v15
	ds_write_b16 v17, v20
	ds_write_b16 v17, v21 offset:272
	ds_write_b16 v17, v22 offset:544
	ds_write_b16 v17, v23 offset:816
	ds_write_b16 v17, v24 offset:1088
	ds_write_b16 v17, v25 offset:1360
	ds_write_b16 v17, v26 offset:1632
	ds_write_b16 v17, v27 offset:1904
	ds_write_b16 v17, v28 offset:2176
	ds_write_b16 v17, v29 offset:2448
	ds_write_b16 v17, v30 offset:2720
	ds_write_b16 v17, v31 offset:2992
	ds_write_b16 v17, v32 offset:3264
	ds_write_b16 v17, v33 offset:3536
	ds_write_b16 v17, v34 offset:3808
	ds_write_b16 v17, v35 offset:4080
	global_store_short v49, v20, s[12:13]
	global_store_short v49, v21, s[12:13] offset:2048
	v_add_u32_e32 v49, 0x1000, v49
	global_store_short v49, v22, s[12:13]
	global_store_short v49, v23, s[12:13] offset:2048
	v_add_u32_e32 v49, 0x1000, v49
	global_store_short v49, v24, s[12:13]
	global_store_short v49, v25, s[12:13] offset:2048
	v_add_u32_e32 v49, 0x1000, v49
	global_store_short v49, v26, s[12:13]
	global_store_short v49, v27, s[12:13] offset:2048
	v_add_u32_e32 v49, 0x1000, v49
	global_store_short v49, v28, s[12:13]
	global_store_short v49, v29, s[12:13] offset:2048
	v_add_u32_e32 v49, 0x1000, v49
	global_store_short v49, v30, s[12:13]
	global_store_short v49, v31, s[12:13] offset:2048
	v_add_u32_e32 v49, 0x1000, v49
	global_store_short v49, v32, s[12:13]
	global_store_short v49, v33, s[12:13] offset:2048
	v_add_u32_e32 v49, 0x1000, v49
	global_store_short v49, v34, s[12:13]
	global_store_short v49, v35, s[12:13] offset:2048
	v_add_u32_e32 v49, 0x1000, v49
	v_add_u32_e32 v17, 0x1100, v17
	v_add_u32_e32 v48, 64, v48
	s_add_i32 s1, s1, 1
	s_cmp_lg_u32 s1, 4
	s_cbranch_scc1 .Lfs_I
	s_branch .LBB0_637

; #define LAS __attribute__((address_space(3)))
; __device__ __forceinline__ float bf2f(unsigned short b) { return __uint_as_float((unsigned)b << 16); }
; __device__ __forceinline__ void scan_load(ScanFrag& f, int n, int b, int h, int ti, int s, int li, int lq, int ucol, const bf16* Qg, const bf16* Kg, const bf16* Vg, const bf16* KT, const bf16* QK, const float* GC) {
;     const int gcid = b * 32 + n, m0 = b * 2048 + n * 64;
;     const bf16* wrow = Kg + (size_t)(m0 + 16 * ti + li) * D + h * 128 + 8 * lq; const bf16* qrow = Qg + (size_t)(m0 + 16 * ti + li) * D + h * 128 + 8 * lq;
; #pragma unroll
;     for (int ks = 0; ks < 4; ++ks) { f.wA[ks] = *(const bf16x8*)(wrow + 32 * ks); f.qA[ks] = *(const bf16x8*)(qrow + 32 * ks); }
;     const bf16* qkrow = QK + ((size_t)(gcid * 8 + h) * 64 + 16 * ti + li) * 64 + 8 * lq; const bf16* ktrow = KT + ((size_t)(gcid * 8 + h) * 128 + 16 * s + li) * 64 + 8 * lq;
; #pragma unroll
;     for (int k2 = 0; k2 < 2; ++k2) { f.qkA[k2] = *(const bf16x8*)(qkrow + 32 * k2); f.kA[k2] = *(const bf16x8*)(ktrow + 32 * k2); }
;     const int rowb = m0 + 16 * ti + 4 * lq;
; #pragma unroll
;     for (int r = 0; r < 4; ++r) { f.uval[r] = bf2f(Vg[(size_t)(rowb + r) * D + ucol]); f.gcr[r] = GC[(size_t)(rowb + r) * 8 + h]; }
;     f.gl = GC[(size_t)(m0 + 63) * 8 + h];
; }
; __device__ __forceinline__ void scan_unit(LAS unsigned char* lds, int uidx, const bf16* Qg, const bf16* Kg, bf16* Vg, const bf16* KT, const bf16* QK, const float* GC, float* SSQ, float* sp_gdn) {
;     const int tid = threadIdx.x, lane = tid & 63, s = __builtin_amdgcn_readfirstlane(tid >> 6);
;     const int xc = uidx & 7, yy = uidx >> 3, slab = yy & 3, bh = xc * 8 + (yy >> 2), b = bh >> 3, h = bh & 7;
;     LAS bf16* St = (LAS bf16*)lds; LAS bf16* Vt = St + 2 * 32 * 136; LAS bf16* Vts = Vt + 32 * 72;
;     const int ti = s >> 1, c = s & 1, li = lane & 15, lq = lane >> 4;
;     f32x4 S0 = (f32x4){0.f, 0.f, 0.f, 0.f}, S1 = S0;
;     const int ucol = h * 128 + slab * 32 + 16 * c + li;
;     ScanFrag cur, nxt;
;     scan_load(cur, 0, b, h, ti, s, li, lq, ucol, Qg, Kg, Vg, KT, QK, GC);
.LBB0_832:
	s_mov_b64 s[0:1], s[56:57]
	s_load_dwordx2 s[0:1], s[0:1], 0x108
	s_mov_b64 s[6:7], s[56:57]
	s_load_dwordx2 s[6:7], s[6:7], 0x108
	s_mov_b64 s[14:15], s[56:57]
	s_waitcnt lgkmcnt(0)
	s_add_u32 s18, s0, 0x4bb0000
	s_addc_u32 s19, s1, 0
	s_mov_b64 s[0:1], s[56:57]
	s_add_u32 s22, s6, 0x6c30000
	s_load_dwordx2 s[20:21], s[14:15], 0x108
	s_addc_u32 s23, s7, 0
	s_load_dwordx2 s[0:1], s[0:1], 0x108
	s_mov_b64 s[6:7], s[56:57]
	s_load_dwordx2 s[6:7], s[6:7], 0x108
	s_mov_b64 s[14:15], s[56:57]
	s_load_dwordx2 s[24:25], s[14:15], 0x108
	s_waitcnt lgkmcnt(0)
	s_add_u32 s28, s0, 0xad30000
	s_addc_u32 s29, s1, 0
	s_add_u32 s30, s6, 0xcdb0000
	s_addc_u32 s31, s7, 0
	s_add_u32 s39, s24, 0xef34000
	s_mov_b64 s[0:1], s[56:57]
	s_addc_u32 s42, s25, 0
	s_lshl_b32 s6, s36, 3
	s_ashr_i32 s7, s36, 5
	s_load_dwordx2 s[26:27], s[0:1], 0x108
	v_readfirstlane_b32 s0, v154
	s_bfe_u32 s1, s36, 0x20003
	s_and_b32 s6, s6, 56
	s_and_b32 s38, s7, 7
	s_add_i32 s6, s6, s7
	s_bfe_u32 s17, s0, 0x10006
	s_lshl_b32 s7, s38, 7
	s_lshl_b32 s37, s1, 5
	s_lshr_b32 s40, s0, 6
	s_ashr_i32 s34, s6, 3
	v_lshl_or_b32 v34, s17, 4, v156
	s_or_b32 s7, s7, s37
	s_lshr_b32 s0, s0, 3
	v_or_b32_e32 v4, s7, v34
	s_lshl_b32 s16, s34, 11
	s_and_b32 s7, s0, 0x1ffffff0
	s_add_i32 s0, s7, s16
	v_or_b32_e32 v76, s0, v70
	v_lshlrev_b32_e32 v68, 1, v4
	v_or_b32_e32 v6, 1, v76
	v_lshl_add_u64 v[4:5], s[20:21], 0, v[68:69]
	v_ashrrev_i32_e32 v77, 31, v76
	v_ashrrev_i32_e32 v7, 31, v6
	v_or_b32_e32 v0, s0, v156
	v_lshl_add_u64 v[74:75], v[4:5], 0, s[10:11]
	v_lshlrev_b64 v[4:5], 11, v[76:77]
	v_lshlrev_b64 v[8:9], 11, v[6:7]
	s_lshl_b32 s20, s34, 8
	s_mov_b64 s[14:15], s[56:57]
	v_ashrrev_i32_e32 v1, 31, v0
	v_lshl_add_u64 v[4:5], v[74:75], 0, v[4:5]
	v_lshl_add_u64 v[8:9], v[74:75], 0, v[8:9]
	s_or_b32 s34, s20, s38
	v_lshlrev_b64 v[0:1], 11, v[0:1]
	v_or_b32_e32 v4, 2, v76
	v_or_b32_e32 v32, 3, v76
	s_ashr_i32 s35, s34, 31
	v_lshl_add_u64 v[2:3], s[22:23], 0, v[0:1]
	s_lshl_b32 s8, s38, 8
	v_lshl_add_u64 v[0:1], s[18:19], 0, v[0:1]
	v_ashrrev_i32_e32 v5, 31, v4
	v_ashrrev_i32_e32 v33, 31, v32
	s_lshl_b64 s[20:21], s[34:35], 6
	v_lshl_add_u64 v[0:1], v[0:1], 0, s[8:9]
	v_lshlrev_b64 v[8:9], 11, v[4:5]
	v_lshlrev_b64 v[10:11], 11, v[32:33]
	s_add_u32 s20, s20, s7
	v_lshl_add_u64 v[2:3], v[2:3], 0, s[8:9]
	v_lshl_add_u64 v[0:1], v[0:1], 0, v[72:73]
	v_lshl_add_u64 v[8:9], v[74:75], 0, v[8:9]
	v_lshl_add_u64 v[10:11], v[74:75], 0, v[10:11]
	s_addc_u32 s21, s21, 0
	v_lshl_add_u64 v[2:3], v[2:3], 0, v[72:73]
	v_mov_b32_e32 v1, s21
	v_or_b32_e32 v0, s20, v156
	s_lshl_b64 s[20:21], s[34:35], 7
	s_lshl_b32 s35, s40, 4
	s_add_u32 s20, s20, s35
	s_addc_u32 s21, s21, 0
	v_lshlrev_b64 v[0:1], 7, v[0:1]
	v_mov_b32_e32 v3, s21
	v_or_b32_e32 v2, s20, v156
	v_lshl_add_u64 v[0:1], s[30:31], 0, v[0:1]
	v_lshlrev_b64 v[2:3], 7, v[2:3]
	s_lshl_b32 s43, s38, 2
	v_lshl_add_u64 v[0:1], v[0:1], 0, v[72:73]
	v_lshl_add_u64 v[2:3], s[28:29], 0, v[2:3]
	s_add_u32 s20, s39, s43
	v_lshl_add_u64 v[2:3], v[2:3], 0, v[72:73]
	s_addc_u32 s21, s42, 0
	v_lshlrev_b64 v[0:1], 5, v[76:77]
	v_lshl_add_u64 v[0:1], s[20:21], 0, v[0:1]
	v_lshlrev_b64 v[0:1], 5, v[6:7]
	v_lshl_add_u64 v[0:1], s[20:21], 0, v[0:1]
	v_lshlrev_b64 v[0:1], 5, v[4:5]
	s_or_b32 s40, s16, 63
	v_lshl_add_u64 v[0:1], s[20:21], 0, v[0:1]
	s_ashr_i32 s41, s40, 31
	v_lshlrev_b64 v[0:1], 5, v[32:33]
	s_lshl_b64 s[40:41], s[40:41], 5
	v_lshl_add_u64 v[0:1], s[20:21], 0, v[0:1]
	s_add_u32 s40, s39, s40
	s_addc_u32 s41, s42, s41
	v_mov_b32_e32 v2, s43
	s_add_u32 s22, s22, s8
	s_addc_u32 s23, s23, 0
	v_mul_u32_u24_e32 v32, 0x48, v34
	s_add_u32 s18, s18, s8
	v_lshlrev_b32_e32 v32, 1, v32
	s_addc_u32 s19, s19, 0
	s_lshl_b32 s8, s7, 1
	v_add_u32_e32 v106, 0, v32
	v_add3_u32 v101, v106, s8, v98
	v_add3_u32 v100, v92, s8, v32
	s_lshl_b32 s8, s38, 5
	s_waitcnt lgkmcnt(0)
; #define LAS __attribute__((address_space(3)))
; __device__ __forceinline__ float bf2f(unsigned short b) { return __uint_as_float((unsigned)b << 16); }
; __device__ __forceinline__ void scan_load(ScanFrag& f, int n, int b, int h, int ti, int s, int li, int lq, int ucol, const bf16* Qg, const bf16* Kg, const bf16* Vg, const bf16* KT, const bf16* QK, const float* GC) {
;     const int gcid = b * 32 + n, m0 = b * 2048 + n * 64;
;     const bf16* wrow = Kg + (size_t)(m0 + 16 * ti + li) * D + h * 128 + 8 * lq; const bf16* qrow = Qg + (size_t)(m0 + 16 * ti + li) * D + h * 128 + 8 * lq;
; #pragma unroll
;     for (int ks = 0; ks < 4; ++ks) { f.wA[ks] = *(const bf16x8*)(wrow + 32 * ks); f.qA[ks] = *(const bf16x8*)(qrow + 32 * ks); }
;     const bf16* qkrow = QK + ((size_t)(gcid * 8 + h) * 64 + 16 * ti + li) * 64 + 8 * lq; const bf16* ktrow = KT + ((size_t)(gcid * 8 + h) * 128 + 16 * s + li) * 64 + 8 * lq;
; #pragma unroll
;     for (int k2 = 0; k2 < 2; ++k2) { f.qkA[k2] = *(const bf16x8*)(qkrow + 32 * k2); f.kA[k2] = *(const bf16x8*)(ktrow + 32 * k2); }
;     const int rowb = m0 + 16 * ti + 4 * lq;
; #pragma unroll
;     for (int r = 0; r < 4; ++r) { f.uval[r] = bf2f(Vg[(size_t)(rowb + r) * D + ucol]); f.gcr[r] = GC[(size_t)(rowb + r) * 8 + h]; }
;     f.gl = GC[(size_t)(m0 + 63) * 8 + h];
; }
; __device__ __forceinline__ void scan_unit(LAS unsigned char* lds, int uidx, const bf16* Qg, const bf16* Kg, bf16* Vg, const bf16* KT, const bf16* QK, const float* GC, float* SSQ, float* sp_gdn) {
;     const int tid = threadIdx.x, lane = tid & 63, s = __builtin_amdgcn_readfirstlane(tid >> 6);
;     const int xc = uidx & 7, yy = uidx >> 3, slab = yy & 3, bh = xc * 8 + (yy >> 2), b = bh >> 3, h = bh & 7;
;     LAS bf16* St = (LAS bf16*)lds; LAS bf16* Vt = St + 2 * 32 * 136; LAS bf16* Vts = Vt + 32 * 72;
;     const int ti = s >> 1, c = s & 1, li = lane & 15, lq = lane >> 4;
;     f32x4 S0 = (f32x4){0.f, 0.f, 0.f, 0.f}, S1 = S0;
;     const int ucol = h * 128 + slab * 32 + 16 * c + li;
;     ScanFrag cur, nxt;
;     scan_load(cur, 0, b, h, ti, s, li, lq, ucol, Qg, Kg, Vg, KT, QK, GC);
;     for (int n = 0; n < 32; ++n) {
;         const int m0 = b * 2048 + n * 64, rowb = m0 + 16 * ti + 4 * lq;
;         __builtin_amdgcn_sched_barrier(0);
;         if (n + 1 < 32) scan_load(nxt, n + 1, b, h, ti, s, li, lq, ucol, Qg, Kg, Vg, KT, QK, GC);
	s_add_u32 s8, s26, s8
	v_lshl_add_u64 v[80:81], s[18:19], 0, v[72:73]
	s_addc_u32 s18, s27, 0
	s_lshl_b32 s1, s1, 3
	s_add_u32 s1, s8, s1
	s_addc_u32 s8, s18, 0
	s_lshl_b32 s17, s17, 2
	s_add_u32 s1, s1, s17
	s_addc_u32 s8, s8, 0
	s_add_u32 s18, s1, 0xefb6000
	s_addc_u32 s19, s8, 0
	s_ashr_i32 s17, s16, 31
	s_lshl_b64 s[26:27], s[16:17], 5
	s_load_dwordx2 s[14:15], s[14:15], 0x100
	v_lshl_add_u64 v[78:79], s[22:23], 0, v[72:73]
	s_or_b32 s22, s34, 8
	s_or_b32 s1, s26, s43
	v_or_b32_e32 v0, s7, v156
	v_mov_b32_e32 v1, v71
	s_add_u32 s1, s24, s1
	v_lshl_add_u64 v[2:3], s[30:31], 0, v[72:73]
	v_or_b32_e32 v4, s35, v156
	v_mov_b32_e32 v5, v71
	v_lshlrev_b64 v[0:1], 7, v[0:1]
	s_addc_u32 s8, s25, s27
	v_lshl_add_u64 v[6:7], s[28:29], 0, v[72:73]
	v_lshl_add_u64 v[82:83], v[2:3], 0, v[0:1]
	v_lshlrev_b64 v[0:1], 7, v[4:5]
	s_add_u32 s24, s1, 0xef34fe0
	v_mul_u32_u24_e32 v105, 0x110, v34
	v_lshl_add_u64 v[84:85], v[6:7], 0, v[0:1]
	s_addc_u32 s25, s8, 0
	v_add_u32_e32 v107, s0, v97
	s_mov_b32 s8, 0
	s_mov_b32 s17, 0
	v_mov_b32_e32 v4, 0
	v_mov_b32_e32 v5, v69
	v_mov_b32_e32 v6, v69
	v_mov_b32_e32 v7, v69
	v_mov_b32_e32 v0, 0
	v_mov_b32_e32 v1, v69
	v_mov_b32_e32 v2, v69
	v_mov_b32_e32 v3, v69
	s_and_b32 s0, s36, 7
	s_bfe_u32 s1, s36, 0x30005
	s_bfe_u32 s22, s36, 0x20003
	s_lshl_b32 s38, s0, 22
	s_lshl_b32 s39, s1, 8
	s_add_u32 s38, s38, s39
	s_add_u32 s24, s86, 0x6c30000
	s_addc_u32 s25, s87, 0
	s_add_u32 s24, s24, s38
	s_addc_u32 s25, s25, 0
	s_add_u32 s26, s86, 0x4bb0000
	s_addc_u32 s27, s87, 0
	s_add_u32 s26, s26, s38
	s_addc_u32 s27, s27, 0
	s_lshl_b32 s39, s22, 6
	s_add_u32 s98, s86, 0x8cb0000
	s_addc_u32 s99, s87, 0
	s_add_u32 s98, s98, s38
	s_addc_u32 s99, s99, 0
	s_add_u32 s98, s98, s39
	s_addc_u32 s99, s99, 0
	s_lshl_b32 s39, s0, 8
	s_add_u32 s39, s39, s1
	s_lshl_b32 s40, s39, 14
	s_add_u32 s28, s86, 0xad30000
	s_addc_u32 s29, s87, 0
	s_add_u32 s28, s28, s40
	s_addc_u32 s29, s29, 0
	s_lshl_b32 s40, s39, 13
	s_add_u32 s30, s86, 0xcdb0000
	s_addc_u32 s31, s87, 0
	s_add_u32 s30, s30, s40
	s_addc_u32 s31, s31, 0
	s_lshl_b32 s40, s0, 16
	s_lshl_b32 s41, s1, 2
	s_add_u32 s40, s40, s41
	s_add_u32 s100, s86, 0xef34000
	s_addc_u32 s101, s87, 0
	s_add_u32 s100, s100, s40
	s_addc_u32 s101, s101, 0
	v_lshrrev_b32_e32 v176, 4, v154
	v_and_b32_e32 v177, 15, v154
	v_lshlrev_b32_e32 v177, 4, v177
	v_lshl_add_u32 v41, v176, 11, v177
	v_add_u32_e32 v42, 0x10000, v41
	v_mul_u32_u24_e32 v47, 0x110, v176
	v_add_u32_e32 v47, v47, v177
	v_add_u32_e32 v47, 0x6800, v47
	v_lshlrev_b32_e32 v43, 4, v154
	v_add_u32_e32 v44, 0x2000, v43
	v_lshrrev_b32_e32 v176, 3, v154
	v_and_b32_e32 v177, 7, v154
	v_lshlrev_b32_e32 v177, 4, v177
	v_mul_u32_u24_e32 v48, 0x90, v176
	v_add_u32_e32 v48, v48, v177
	v_add_u32_e32 v48, 0xf000, v48
	v_bfe_u32 v176, v154, 2, 6
	v_and_b32_e32 v177, 3, v154
	v_lshlrev_b32_e32 v177, 4, v177
	v_lshl_add_u32 v45, v176, 11, v177
	v_mul_u32_u24_e32 v49, 0x50, v176
	v_add_u32_e32 v49, v49, v177
	v_add_u32_e32 v49, 0x15c00, v49
	v_and_b32_e32 v176, 63, v154
	v_lshlrev_b32_e32 v46, 5, v176
	v_lshlrev_b32_e32 v50, 2, v176
	v_add_u32_e32 v50, 0x17000, v50
	v_lshrrev_b32_e32 v176, 7, v154
	v_and_b32_e32 v177, 15, v154
	v_lshl_add_u32 v176, v176, 4, v177
	v_bfe_u32 v178, v154, 4, 2
	v_lshlrev_b32_e32 v179, 4, v178
	v_mul_u32_u24_e32 v51, 0x110, v176
	v_add_u32_e32 v51, v51, v179
	v_add_u32_e32 v51, 0x6800, v51
	v_mul_u32_u24_e32 v52, 0x90, v176
	v_add_u32_e32 v52, v52, v179
	v_add_u32_e32 v52, 0x13800, v52
	v_lshrrev_b32_e32 v180, 6, v154
	v_lshl_add_u32 v180, v180, 4, v177
	v_mul_u32_u24_e32 v53, 0x90, v180
	v_add_u32_e32 v53, v53, v179
	v_add_u32_e32 v53, 0xf000, v53
	v_lshrrev_b32_e32 v180, 7, v154
	v_lshlrev_b32_e32 v180, 4, v180
	v_lshl_add_u32 v180, v178, 2, v180
	v_mul_u32_u24_e32 v54, 0x50, v180
	v_bfe_u32 v181, v154, 6, 1
	v_lshl_add_u32 v181, v181, 4, v177
	v_lshl_add_u32 v54, v181, 1, v54
	v_add_u32_e32 v54, 0x15c00, v54
	v_lshlrev_b32_e32 v55, 2, v180
	v_add_u32_e32 v55, 0x17000, v55
	v_mov_b32_e32 v174, 0x170fc
	global_load_dwordx4 v[8:11], v41, s[24:25]
	global_load_dwordx4 v[12:15], v42, s[24:25]
	global_load_dwordx4 v[16:19], v41, s[26:27]
	global_load_dwordx4 v[20:23], v42, s[26:27]
	global_load_dwordx4 v[24:27], v43, s[28:29]
	global_load_dwordx4 v[28:31], v44, s[28:29]
	global_load_dwordx4 v[32:35], v43, s[30:31]
	global_load_dwordx4 v[36:39], v45, s[98:99]
	global_load_dword v40, v46, s[100:101]
	s_waitcnt vmcnt(0)
	ds_write_b128 v47, v[8:11]
	ds_write_b128 v47, v[12:15] offset:8704
	ds_write_b128 v47, v[16:19] offset:17408
	ds_write_b128 v47, v[20:23] offset:26112
	ds_write_b128 v48, v[24:27]
	ds_write_b128 v48, v[28:31] offset:9216
	ds_write_b128 v48, v[32:35] offset:18432
	ds_write_b128 v49, v[36:39]
	ds_write_b32 v50, v40
	s_add_u32 s24, s24, 0x20000
	s_addc_u32 s25, s25, 0
	s_add_u32 s26, s26, 0x20000
	s_addc_u32 s27, s27, 0
	s_add_u32 s28, s28, 0x20000
	s_addc_u32 s29, s29, 0
	s_add_u32 s30, s30, 0x10000
	s_addc_u32 s31, s31, 0
	s_add_u32 s98, s98, 0x20000
	s_addc_u32 s99, s99, 0
	s_add_u32 s100, s100, 0x800
	s_addc_u32 s101, s101, 0
	global_load_dwordx4 v[8:11], v41, s[24:25]
	global_load_dwordx4 v[12:15], v42, s[24:25]
	global_load_dwordx4 v[16:19], v41, s[26:27]
	global_load_dwordx4 v[20:23], v42, s[26:27]
	global_load_dwordx4 v[24:27], v43, s[28:29]
	global_load_dwordx4 v[28:31], v44, s[28:29]
	global_load_dwordx4 v[32:35], v43, s[30:31]
	global_load_dwordx4 v[36:39], v45, s[98:99]
	global_load_dword v40, v46, s[100:101]
	s_add_u32 s24, s24, 0x20000
	s_addc_u32 s25, s25, 0
	s_add_u32 s26, s26, 0x20000
	s_addc_u32 s27, s27, 0
	s_add_u32 s28, s28, 0x20000
	s_addc_u32 s29, s29, 0
	s_add_u32 s30, s30, 0x10000
	s_addc_u32 s31, s31, 0
	s_add_u32 s98, s98, 0x20000
	s_addc_u32 s99, s99, 0
	s_add_u32 s100, s100, 0x800
	s_addc_u32 s101, s101, 0
	global_load_dwordx4 v[184:187], v41, s[24:25]
	global_load_dwordx4 v[188:191], v42, s[24:25]
	global_load_dwordx4 v[192:195], v41, s[26:27]
	global_load_dwordx4 v[196:199], v42, s[26:27]
	global_load_dwordx4 v[200:203], v43, s[28:29]
	global_load_dwordx4 v[204:207], v44, s[28:29]
	global_load_dwordx4 v[208:211], v43, s[30:31]
	global_load_dwordx4 v[212:215], v45, s[98:99]
	global_load_dword v216, v46, s[100:101]

; #define LAS __attribute__((address_space(3)))
; __device__ __forceinline__ void scan_unit(LAS unsigned char* lds, int uidx, const bf16* Qg, const bf16* Kg, bf16* Vg, const bf16* KT, const bf16* QK, const float* GC, float* SSQ, float* sp_gdn) {
;     ...
;     for (int n = 0; n < 32; ++n) {
;         const int m0 = b * 2048 + n * 64, rowb = m0 + 16 * ti + 4 * lq;
;         __builtin_amdgcn_sched_barrier(0);
;         if (n + 1 < 32) scan_load(nxt, n + 1, b, h, ti, s, li, lq, ucol, Qg, Kg, Vg, KT, QK, GC);
;         __builtin_amdgcn_sched_barrier(0);
;         const bf16x8 (&wA)[4] = cur.wA; const bf16x8 (&qA)[4] = cur.qA; const bf16x8 (&qkA)[2] = cur.qkA; const bf16x8 (&kA)[2] = cur.kA;
;         const float (&uval)[4] = cur.uval; const float (&gcr)[4] = cur.gcr; const float gl = cur.gl;
;         LAS bf16* Sb = St + (n & 1) * 32 * 136;
;         { u32x2 w; w.x = cvt_pk_bf16(S0[0], S0[1]); w.y = cvt_pk_bf16(S0[2], S0[3]); *(LAS u32x2*)(Sb + li * 136 + 16 * s + 4 * lq) = w;
;           w.x = cvt_pk_bf16(S1[0], S1[1]); w.y = cvt_pk_bf16(S1[2], S1[3]); *(LAS u32x2*)(Sb + (16 + li) * 136 + 16 * s + 4 * lq) = w; }
;         LDS_BARRIER();
;         bf16x8 bS[4]; f32x4 acc = (f32x4){0.f, 0.f, 0.f, 0.f};
; #pragma unroll
;         for (int ks = 0; ks < 4; ++ks) { bS[ks] = *(const LAS bf16x8*)(Sb + (16 * c + li) * 136 + 32 * ks + 8 * lq); acc = __builtin_amdgcn_mfma_f32_16x16x32_bf16(wA[ks], bS[ks], acc, 0, 0, 0); }
;         f32x4 o = (f32x4){0.f, 0.f, 0.f, 0.f};
; #pragma unroll
;         for (int ks = 0; ks < 4; ++ks) o = __builtin_amdgcn_mfma_f32_16x16x32_bf16(qA[ks], bS[ks], o, 0, 0, 0);
;         { float vn[4], vs[4];
; #pragma unroll
;           for (int r = 0; r < 4; ++r) { vn[r] = uval[r] - acc[r]; vs[r] = vn[r] * __expf(gl - gcr[r]); }
;           u32x2 w; w.x = cvt_pk_bf16(vn[0], vn[1]); w.y = cvt_pk_bf16(vn[2], vn[3]); *(LAS u32x2*)(Vt + (16 * c + li) * 72 + 16 * ti + 4 * lq) = w;
;           w.x = cvt_pk_bf16(vs[0], vs[1]); w.y = cvt_pk_bf16(vs[2], vs[3]); *(LAS u32x2*)(Vts + (16 * c + li) * 72 + 16 * ti + 4 * lq) = w; }
;         LDS_BARRIER();
; #pragma unroll
;         for (int r = 0; r < 4; ++r) o[r] *= __expf(gcr[r]);
; #pragma unroll
;         for (int k2 = 0; k2 < 2; ++k2) { const bf16x8 bV = *(const LAS bf16x8*)(Vt + (16 * c + li) * 72 + 32 * k2 + 8 * lq); o = __builtin_amdgcn_mfma_f32_16x16x32_bf16(qkA[k2], bV, o, 0, 0, 0); }
; #pragma unroll
.LBB0_841:
	s_or_b64 exec, exec, s[0:1]
	v_mul_f32_e32 v64, 0x3fb8aa3b, v108
	v_exp_f32_e32 v108, v64
	ds_read_b128 v[64:67], v99 offset:22016
	ds_read_b128 v[86:89], v99 offset:24320
	ds_read_b128 v[114:117], v99 offset:22080
	ds_read_b128 v[118:121], v99 offset:24384
	v_pk_mul_f32 v[6:7], v[6:7], v[108:109] op_sel_hi:[1,0]
	v_pk_mul_f32 v[4:5], v[4:5], v[108:109] op_sel_hi:[1,0]
	v_pk_mul_f32 v[2:3], v[2:3], v[108:109] op_sel_hi:[1,0]
	v_pk_mul_f32 v[0:1], v[0:1], v[108:109] op_sel_hi:[1,0]
	s_waitcnt lgkmcnt(3)
	v_mfma_f32_16x16x32_bf16 v[4:7], v[60:63], v[64:67], v[4:7]
	s_waitcnt lgkmcnt(2)
	v_mfma_f32_16x16x32_bf16 v[0:3], v[60:63], v[86:89], v[0:3]
	s_waitcnt lgkmcnt(1)
	v_mfma_f32_16x16x32_bf16 v[4:7], v[56:59], v[114:117], v[4:7]
	s_waitcnt lgkmcnt(0)
	v_mfma_f32_16x16x32_bf16 v[0:3], v[56:59], v[118:121], v[0:3]
	s_cmpk_gt_u32 s8, 0x780
	s_cbranch_scc1 .LscanA_nostage
	s_cmpk_gt_u32 s8, 0x700
	s_cbranch_scc1 .LscanA_strict
	s_waitcnt vmcnt(17)
	s_branch .LscanA_wr
.LscanA_strict:
	s_waitcnt vmcnt(8)
.LscanA_wr:
	ds_write_b128 v47, v[8:11]
	ds_write_b128 v47, v[12:15] offset:8704
	ds_write_b128 v47, v[16:19] offset:17408
	ds_write_b128 v47, v[20:23] offset:26112
	ds_write_b128 v48, v[24:27]
	ds_write_b128 v48, v[28:31] offset:9216
	ds_write_b128 v48, v[32:35] offset:18432
	ds_write_b128 v49, v[36:39]
	ds_write_b32 v50, v40
	s_cmpk_gt_u32 s8, 0x700
	s_cbranch_scc1 .LscanA_nostage
	s_add_u32 s24, s24, 0x20000
	s_addc_u32 s25, s25, 0
	s_add_u32 s26, s26, 0x20000
	s_addc_u32 s27, s27, 0
	s_add_u32 s28, s28, 0x20000
	s_addc_u32 s29, s29, 0
	s_add_u32 s30, s30, 0x10000
	s_addc_u32 s31, s31, 0
	s_add_u32 s98, s98, 0x20000
	s_addc_u32 s99, s99, 0
	s_add_u32 s100, s100, 0x800
	s_addc_u32 s101, s101, 0
	global_load_dwordx4 v[8:11], v41, s[24:25]
	global_load_dwordx4 v[12:15], v42, s[24:25]
	global_load_dwordx4 v[16:19], v41, s[26:27]
	global_load_dwordx4 v[20:23], v42, s[26:27]
	global_load_dwordx4 v[24:27], v43, s[28:29]
	global_load_dwordx4 v[28:31], v44, s[28:29]
	global_load_dwordx4 v[32:35], v43, s[30:31]
	global_load_dwordx4 v[36:39], v45, s[98:99]
	global_load_dword v40, v46, s[100:101]
.LscanA_nostage:
	s_add_i32 s17, s17, 32
	s_add_i32 s8, s8, 64
.Lscan_bodyB:
	v_add_u32_e32 v86, s8, v76
	s_and_b32 s0, s17, 32
	s_mulk_i32 s0, 0x110
	s_add_i32 s0, s0, 0
	s_lshl_b32 s23, s35, 1
	s_add_i32 s1, s23, s0
	v_cvt_pk_bf16_f32 v88, v4, v5
	v_cvt_pk_bf16_f32 v89, v6, v7
	v_add3_u32 v150, s1, v90, v98
	ds_write_b64 v150, v[88:89]
	v_cvt_pk_bf16_f32 v88, v0, v1
	v_cvt_pk_bf16_f32 v89, v2, v3
	v_add3_u32 v150, s1, v91, v98
	ds_write_b64 v150, v[88:89]
	s_waitcnt lgkmcnt(0)
	s_barrier
	v_add3_u32 v88, s0, v105, v94
	ds_read_b128 v[162:165], v88
	ds_read_b128 v[166:169], v88 offset:64
	ds_read_b128 v[176:179], v55
	ds_read_b32 v108, v174
	ds_read_u16 v180, v54
	ds_read_u16 v181, v54 offset:80
	ds_read_u16 v182, v54 offset:160
	ds_read_u16 v183, v54 offset:240
	ds_read_b128 v[114:117], v51
	ds_read_b128 v[118:121], v51 offset:64
	ds_read_b128 v[122:125], v51 offset:128
	ds_read_b128 v[126:129], v51 offset:192
	s_waitcnt lgkmcnt(0)
	v_mov_b32_e32 v87, v176
	v_mov_b32_e32 v110, v177
	v_mov_b32_e32 v153, v178
	v_mov_b32_e32 v155, v179
	v_lshlrev_b32_e32 v66, 16, v180
	v_lshlrev_b32_e32 v67, 16, v181
	v_lshlrev_b32_e32 v64, 16, v182
	v_lshlrev_b32_e32 v65, 16, v183
	v_mfma_f32_16x16x32_bf16 v[114:117], v[114:117], v[162:165], 0
	v_sub_f32_e32 v89, v108, v110
	v_mul_f32_e32 v89, 0x3fb8aa3b, v89
	v_exp_f32_e32 v89, v89
	v_mfma_f32_16x16x32_bf16 v[114:117], v[118:121], v[166:169], v[114:117]
	ds_read_b128 v[118:121], v88 offset:128
	ds_read_b128 v[170:173], v88 offset:192
	ds_read_b128 v[130:133], v51 offset:17408
	ds_read_b128 v[134:137], v51 offset:17472
	ds_read_b128 v[138:141], v51 offset:17536
	ds_read_b128 v[142:145], v51 offset:17600
	ds_read_b128 v[146:149], v52
	ds_read_b128 v[158:161], v52 offset:64
	ds_read_b128 v[60:63], v53
	ds_read_b128 v[56:59], v53 offset:64
	v_sub_f32_e32 v88, v108, v87
	v_mul_f32_e32 v88, 0x3fb8aa3b, v88
	s_waitcnt lgkmcnt(9)
	v_mfma_f32_16x16x32_bf16 v[114:117], v[122:125], v[118:121], v[114:117]
	v_exp_f32_e32 v88, v88
	s_waitcnt lgkmcnt(7)
	v_mfma_f32_16x16x32_bf16 v[122:125], v[130:133], v[162:165], 0
	v_mfma_f32_16x16x32_bf16 v[114:117], v[126:129], v[170:173], v[114:117]
	v_sub_f32_e32 v126, v108, v153
	v_sub_f32_e32 v127, v108, v155
	v_mul_f32_e32 v126, 0x3fb8aa3b, v126
	v_mul_f32_e32 v127, 0x3fb8aa3b, v127
	v_exp_f32_e32 v126, v126
	v_exp_f32_e32 v127, v127
	s_waitcnt lgkmcnt(6)
	v_mfma_f32_16x16x32_bf16 v[122:125], v[134:137], v[166:169], v[122:125]
	s_nop 0
	v_add_f32_e64 v66, v66, -v114
	v_add_f32_e64 v67, v67, -v115
	v_pk_add_f32 v[64:65], v[64:65], v[116:117] neg_lo:[0,1] neg_hi:[0,1]
	v_pk_mul_f32 v[88:89], v[88:89], v[66:67]
	v_pk_mul_f32 v[114:115], v[126:127], v[64:65]
	s_waitcnt lgkmcnt(5)
	v_mfma_f32_16x16x32_bf16 v[118:121], v[138:141], v[118:121], v[122:125]
	v_cvt_pk_bf16_f32 v66, v66, v67
	v_cvt_pk_bf16_f32 v88, v88, v89
	v_cvt_pk_bf16_f32 v67, v64, v65
	v_cvt_pk_bf16_f32 v89, v114, v115
	v_mul_f32_e32 v64, 0x3fb8aa3b, v87
	ds_write_b64 v100, v[88:89] offset:22016
	v_exp_f32_e32 v88, v64
	v_mul_f32_e32 v64, 0x3fb8aa3b, v110
	ds_write_b64 v101, v[66:67] offset:17408
	v_exp_f32_e32 v89, v64
	v_mul_f32_e32 v64, 0x3fb8aa3b, v153
	s_waitcnt lgkmcnt(0)
	s_barrier
	v_exp_f32_e32 v122, v64
	v_mul_f32_e32 v64, 0x3fb8aa3b, v155
	v_add_u32_e32 v110, v106, v94
	v_exp_f32_e32 v123, v64
	ds_read_b128 v[64:67], v110 offset:17408
	v_mfma_f32_16x16x32_bf16 v[114:117], v[142:145], v[170:173], v[118:121]
	v_ashrrev_i32_e32 v87, 31, v86
	s_nop 1
	ds_read_b128 v[118:121], v110 offset:17472
	s_nop 3
	v_pk_mul_f32 v[114:115], v[88:89], v[114:115]
	v_pk_mul_f32 v[116:117], v[122:123], v[116:117]
	v_lshlrev_b64 v[88:89], 11, v[86:87]
	v_lshl_add_u64 v[88:89], v[74:75], 0, v[88:89]
	s_waitcnt lgkmcnt(1)
	v_mfma_f32_16x16x32_bf16 v[64:67], v[146:149], v[64:67], v[114:117]
	s_waitcnt lgkmcnt(0)
	v_mfma_f32_16x16x32_bf16 v[64:67], v[158:161], v[118:121], v[64:67]
	s_nop 7
	v_cvt_pk_bf16_f32 v114, v64, s0
	global_store_short v[88:89], v114, off
	v_mul_f32_e32 v88, v64, v64
	s_nop 1
	v_mov_b32_dpp v88, v88 row_ror:8 row_mask:0xf bank_mask:0xf bound_ctrl:1
	v_fmac_f32_e32 v88, v64, v64
	s_nop 1
	v_add_f32_dpp v64, v88, v88 row_ror:4 row_mask:0xf bank_mask:0xf bound_ctrl:1
	s_nop 1
	v_add_f32_dpp v64, v64, v64 row_ror:2 row_mask:0xf bank_mask:0xf bound_ctrl:1
	s_nop 1
	v_mov_b32_dpp v88, v64 row_ror:1 row_mask:0xf bank_mask:0xf bound_ctrl:1
	s_and_saveexec_b64 s[0:1], vcc
	s_cbranch_execz .LscanB_835
	v_add_f32_e32 v64, v64, v88
	v_lshlrev_b64 v[88:89], 8, v[86:87]
	v_lshl_add_u64 v[88:89], s[18:19], 0, v[88:89]
	global_store_dword v[88:89], v64, off

; #define LAS __attribute__((address_space(3)))
; __device__ __forceinline__ float bf2f(unsigned short b) { return __uint_as_float((unsigned)b << 16); }
; __device__ __forceinline__ void scan_load(ScanFrag& f, int n, int b, int h, int ti, int s, int li, int lq, int ucol, const bf16* Qg, const bf16* Kg, const bf16* Vg, const bf16* KT, const bf16* QK, const float* GC) {
;     const int gcid = b * 32 + n, m0 = b * 2048 + n * 64;
;     const bf16* wrow = Kg + (size_t)(m0 + 16 * ti + li) * D + h * 128 + 8 * lq; const bf16* qrow = Qg + (size_t)(m0 + 16 * ti + li) * D + h * 128 + 8 * lq;
; #pragma unroll
;     for (int ks = 0; ks < 4; ++ks) { f.wA[ks] = *(const bf16x8*)(wrow + 32 * ks); f.qA[ks] = *(const bf16x8*)(qrow + 32 * ks); }
;     const bf16* qkrow = QK + ((size_t)(gcid * 8 + h) * 64 + 16 * ti + li) * 64 + 8 * lq; const bf16* ktrow = KT + ((size_t)(gcid * 8 + h) * 128 + 16 * s + li) * 64 + 8 * lq;
; #pragma unroll
;     for (int k2 = 0; k2 < 2; ++k2) { f.qkA[k2] = *(const bf16x8*)(qkrow + 32 * k2); f.kA[k2] = *(const bf16x8*)(ktrow + 32 * k2); }
;     const int rowb = m0 + 16 * ti + 4 * lq;
; #pragma unroll
;     for (int r = 0; r < 4; ++r) { f.uval[r] = bf2f(Vg[(size_t)(rowb + r) * D + ucol]); f.gcr[r] = GC[(size_t)(rowb + r) * 8 + h]; }
;     f.gl = GC[(size_t)(m0 + 63) * 8 + h];
; }
; __device__ __forceinline__ void scan_unit(LAS unsigned char* lds, int uidx, const bf16* Qg, const bf16* Kg, bf16* Vg, const bf16* KT, const bf16* QK, const float* GC, float* SSQ, float* sp_gdn) {
;     const int tid = threadIdx.x, lane = tid & 63, s = __builtin_amdgcn_readfirstlane(tid >> 6);
;     const int xc = uidx & 7, yy = uidx >> 3, slab = yy & 3, bh = xc * 8 + (yy >> 2), b = bh >> 3, h = bh & 7;
;     LAS bf16* St = (LAS bf16*)lds; LAS bf16* Vt = St + 2 * 32 * 136; LAS bf16* Vts = Vt + 32 * 72;
;     const int ti = s >> 1, c = s & 1, li = lane & 15, lq = lane >> 4;
;     f32x4 S0 = (f32x4){0.f, 0.f, 0.f, 0.f}, S1 = S0;
;     const int ucol = h * 128 + slab * 32 + 16 * c + li;
;     ScanFrag cur, nxt;
;     scan_load(cur, 0, b, h, ti, s, li, lq, ucol, Qg, Kg, Vg, KT, QK, GC);
;     for (int n = 0; n < 32; ++n) {
;         const int m0 = b * 2048 + n * 64, rowb = m0 + 16 * ti + 4 * lq;
;         __builtin_amdgcn_sched_barrier(0);
;         if (n + 1 < 32) scan_load(nxt, n + 1, b, h, ti, s, li, lq, ucol, Qg, Kg, Vg, KT, QK, GC);
.LscanB_wr:
	ds_write_b128 v47, v[184:187]
	ds_write_b128 v47, v[188:191] offset:8704
	ds_write_b128 v47, v[192:195] offset:17408
	ds_write_b128 v47, v[196:199] offset:26112
	ds_write_b128 v48, v[200:203]
	ds_write_b128 v48, v[204:207] offset:9216
	ds_write_b128 v48, v[208:211] offset:18432
	ds_write_b128 v49, v[212:215]
	ds_write_b32 v50, v216
	s_cmpk_gt_u32 s8, 0x700
	s_cbranch_scc1 .LscanB_nostage
	s_add_u32 s24, s24, 0x20000
	s_addc_u32 s25, s25, 0
	s_add_u32 s26, s26, 0x20000
	s_addc_u32 s27, s27, 0
	s_add_u32 s28, s28, 0x20000
	s_addc_u32 s29, s29, 0
	s_add_u32 s30, s30, 0x10000
	s_addc_u32 s31, s31, 0
	s_add_u32 s98, s98, 0x20000
	s_addc_u32 s99, s99, 0
	s_add_u32 s100, s100, 0x800
	s_addc_u32 s101, s101, 0
	global_load_dwordx4 v[184:187], v41, s[24:25]
	global_load_dwordx4 v[188:191], v42, s[24:25]
	global_load_dwordx4 v[192:195], v41, s[26:27]
	global_load_dwordx4 v[196:199], v42, s[26:27]
	global_load_dwordx4 v[200:203], v43, s[28:29]
	global_load_dwordx4 v[204:207], v44, s[28:29]
	global_load_dwordx4 v[208:211], v43, s[30:31]
	global_load_dwordx4 v[212:215], v45, s[98:99]
	global_load_dword v216, v46, s[100:101]
